# scan: INV role's overlapping LDS loads narrowed (no in-burst lgkmcnt(0) round trips), E roles' stale lgkmcnt guards removed
# speedup vs baseline: 1.0119x; 1.0119x over previous
.LBB0_718:
	s_mov_b64 s[4:5], -1
	s_mov_b64 s[10:11], 0
	s_cmp_lt_i32 s70, 5
	s_mov_b64 s[46:47], 0
	s_barrier
	s_cbranch_scc1 .LBB0_770
	s_cmp_gt_i32 s70, 5
	s_cbranch_scc0 .LBB0_754
	s_cmp_gt_i32 s70, 6
	s_cbranch_scc0 .LBB0_738
	s_cmp_eq_u32 s70, 7
	s_mov_b64 s[46:47], -1
	s_cbranch_scc0 .LBB0_737
	v_lshlrev_b32_e32 v5, 1, v148
	s_add_i32 s4, 0, 0x19c00
	v_add_u32_e32 v2, s4, v5
	ds_read_u16 v29, v2 offset:6656
	ds_read_u16 v42, v2 offset:6784
	ds_read_u16 v43, v2 offset:6912
	ds_read_u16 v44, v2 offset:7040
	ds_read_u16 v45, v2 offset:7168
	ds_read_u16 v46, v2 offset:7296
	ds_read_u16 v47, v2 offset:7424
	ds_read_u16 v48, v2 offset:7552
	v_add_u32_e32 v3, s4, v148
	ds_read_u16 v49, v2 offset:7680
	ds_read_u16 v50, v2 offset:7808
	ds_read_u16 v51, v2 offset:7936
	ds_read_u16 v52, v2 offset:8064
	ds_read_u8 v1, v3 offset:9024
	ds_read_u8 v9, v3 offset:9152
	ds_read_u8 v0, v3 offset:9088
	ds_read_u8 v8, v3 offset:8960
	ds_read_u16 v59, v2 offset:1536
	ds_read_u16 v12, v2 offset:3584
	ds_read_u16 v62, v2 offset:1664
	ds_read_u16 v13, v2 offset:3712
	ds_read_u16 v65, v2 offset:1792
	ds_read_u16 v14, v2 offset:3840
	ds_read_u16 v15, v2 offset:3968
	ds_read_u16 v68, v2 offset:1920
	ds_read_u16 v69, v2 offset:6144
	ds_read_u16 v70, v2 offset:6272
	ds_read_u16 v71, v2 offset:6400
	ds_read_u16 v72, v2 offset:6528
	ds_read_u16 v73, v2 offset:5632
	ds_read_u16 v75, v2 offset:5760
	ds_read_u16 v77, v2 offset:5888
	ds_read_u16 v79, v2 offset:6016
	s_add_i32 s4, 0, 0x1c4c0
	v_mov_b32_e32 v7, s4
	s_add_i32 s4, 0, 0x1c4d0
	v_mov_b32_e32 v3, s4
	s_add_i32 s4, 0, 0x1c4e0
	v_mov_b32_e32 v10, s4
	s_add_i32 s4, 0, 0x1c4f0
	v_mov_b32_e32 v11, s4
	ds_read_b32 v2, v7
	ds_read_b32 v3, v3
	ds_read_b32 v10, v10
	ds_read_b32 v11, v11
	v_and_b32_e32 v7, 1, v128
	v_lshrrev_b32_e32 v16, 1, v128
	v_cmp_eq_u32_e64 s[6:7], 0, v7
	v_and_b32_e32 v7, 50, v128
	v_and_b32_e32 v5, 8, v5
	v_and_b32_e32 v16, 4, v16
	v_or3_b32 v53, v16, v7, v5
	v_and_b32_e32 v5, 32, v128
	v_and_b32_e32 v7, 31, v128
	s_mov_b32 s13, 0
	v_mul_u32_u24_e32 v54, 0x50, v148
	v_mul_u32_u24_e32 v55, 48, v5
	v_mul_u32_u24_e32 v56, 48, v7
	v_mov_b32_e32 v5, v4
	v_mov_b32_e32 v7, v6
	s_mov_b32 s12, 0x3b808081
	s_waitcnt lgkmcnt(0)
	s_branch .LBB0_725

.LBB0_727:
	v_cndmask_b32_e64 v28, 0, 1, s[14:15]
	v_cmp_ne_u32_e64 s[8:9], 1, v28
	s_andn2_b64 vcc, exec, s[14:15]
	s_cbranch_vccnz .LBB0_731
	v_lshlrev_b32_e32 v28, 16, v69
	v_add_f32_e32 v28, 0, v28
	v_lshlrev_b32_e32 v30, 16, v70
	v_add_f32_e32 v28, v28, v30
	v_lshlrev_b32_e32 v30, 16, v71
	v_add_f32_e32 v28, v28, v30
	v_lshlrev_b32_e32 v30, 16, v72
	v_add_f32_e32 v28, v28, v30
	v_lshlrev_b32_e32 v30, 16, v29
	v_add_f32_e32 v28, v28, v30
	v_lshlrev_b32_e32 v30, 16, v42
	v_add_f32_e32 v28, v28, v30
	v_lshlrev_b32_e32 v30, 16, v43
	v_add_f32_e32 v28, v28, v30
	v_lshlrev_b32_e32 v30, 16, v44
	v_add_f32_e32 v28, v28, v30
	v_lshlrev_b32_e32 v30, 16, v45
	v_add_f32_e32 v28, v28, v30
	v_lshlrev_b32_e32 v30, 16, v46
	v_add_f32_e32 v28, v28, v30
	v_lshlrev_b32_e32 v30, 16, v47
	v_add_f32_e32 v28, v28, v30
	v_lshlrev_b32_e32 v30, 16, v48
	v_add_f32_e32 v30, v28, v30
	v_lshlrev_b32_e32 v28, 16, v49
	v_add_f32_e32 v31, v30, v28
	v_lshlrev_b32_e32 v28, 16, v50
	v_add_f32_e32 v40, v31, v28
	v_lshlrev_b32_e32 v28, 16, v51
	v_exp_f32_e32 v101, v31
	v_cvt_f32_u32_e32 v37, v1
	v_cvt_f32_u32_e32 v36, v8
	v_add_f32_e32 v109, v40, v28
	v_lshlrev_b32_e32 v28, 16, v52
	v_add_f32_e32 v28, v109, v28
	v_exp_f32_e32 v28, v28
	v_exp_f32_e32 v41, v30
	v_lshlrev_b32_e32 v32, 16, v59
	v_exp_f32_e32 v111, v40
	v_exp_f32_e32 v120, v109
	v_lshlrev_b32_e32 v35, 16, v13
	v_lshlrev_b32_e32 v34, 16, v12
	v_mul_f32_e32 v93, v101, v32
	v_pk_mul_f32 v[32:33], v[36:37], s[12:13] op_sel_hi:[1,0]
	v_pk_fma_f32 v[36:37], v[36:37], s[12:13], -1.0 op_sel_hi:[1,0,0]
	v_cvt_f32_u32_e32 v117, v9
	v_cvt_f32_u32_e32 v116, v0
	v_pk_mul_f32 v[38:39], v[4:5], v[34:35]
	v_pk_fma_f32 v[36:37], v[6:7], v[36:37], 1.0 op_sel_hi:[1,1,0]
	v_pk_mul_f32 v[38:39], v[38:39], v[2:3]
	v_pk_mul_f32 v[34:35], v[36:37], v[34:35]
	v_lshlrev_b32_e32 v37, 16, v65
	v_rcp_f32_e32 v30, v101
	v_mul_f32_e32 v95, v41, v38
	v_rcp_f32_e32 v31, v111
	v_lshlrev_b32_e32 v41, 16, v15
	v_lshlrev_b32_e32 v40, 16, v14
	v_rcp_f32_e32 v36, v120
	v_mul_f32_e32 v109, v120, v37
	v_rcp_f32_e32 v37, v28
	v_pk_mul_f32 v[32:33], v[32:33], v[38:39]
	v_mul_f32_e32 v101, v101, v39
	v_pk_mul_f32 v[38:39], v[116:117], s[12:13] op_sel_hi:[1,0]
	v_pk_mul_f32 v[112:113], v[4:5], v[40:41]
	v_pk_fma_f32 v[116:117], v[116:117], s[12:13], -1.0 op_sel_hi:[1,0,0]
	v_pk_mul_f32 v[118:119], v[112:113], v[10:11]
	v_pk_fma_f32 v[116:117], v[6:7], v[116:117], 1.0 op_sel_hi:[1,1,0]
	s_and_b32 s4, s13, 2
	v_lshlrev_b32_e32 v102, 16, v62
	v_lshlrev_b32_e32 v121, 16, v68
	v_pk_mul_f32 v[38:39], v[38:39], v[118:119]
	v_pk_mul_f32 v[40:41], v[116:117], v[40:41]
	s_mulk_i32 s4, 0x5f00
	v_mul_f32_e32 v97, v30, v32
	v_mul_f32_e32 v99, v30, v34
	v_mul_f32_e32 v102, v111, v102
	v_mul_f32_e32 v103, v31, v33
	v_mul_f32_e32 v105, v31, v35
	v_mul_f32_e32 v111, v111, v118
	v_mul_f32_e32 v113, v36, v38
	v_mul_f32_e32 v115, v36, v40
	v_mul_f32_e32 v117, v120, v119
	v_mul_f32_e32 v118, v28, v121
	v_mul_f32_e32 v119, v37, v39
	v_mul_f32_e32 v121, v37, v41
	s_add_i32 s14, s4, 0
	v_mov_b32_dpp v94, v93 quad_perm:[1,1,3,3] row_mask:0xf bank_mask:0xf bound_ctrl:1
	v_mov_b32_dpp v96, v95 quad_perm:[1,1,3,3] row_mask:0xf bank_mask:0xf bound_ctrl:1
	v_mov_b32_dpp v98, v97 quad_perm:[1,1,3,3] row_mask:0xf bank_mask:0xf bound_ctrl:1
	v_mov_b32_dpp v100, v99 quad_perm:[1,1,3,3] row_mask:0xf bank_mask:0xf bound_ctrl:1
	v_mov_b32_dpp v104, v101 quad_perm:[1,1,3,3] row_mask:0xf bank_mask:0xf bound_ctrl:1
	v_mov_b32_dpp v106, v102 quad_perm:[1,1,3,3] row_mask:0xf bank_mask:0xf bound_ctrl:1
	v_mov_b32_dpp v107, v103 quad_perm:[1,1,3,3] row_mask:0xf bank_mask:0xf bound_ctrl:1
	v_mov_b32_dpp v108, v105 quad_perm:[1,1,3,3] row_mask:0xf bank_mask:0xf bound_ctrl:1
	v_mov_b32_dpp v110, v109 quad_perm:[1,1,3,3] row_mask:0xf bank_mask:0xf bound_ctrl:1
	v_mov_b32_dpp v112, v111 quad_perm:[1,1,3,3] row_mask:0xf bank_mask:0xf bound_ctrl:1
	v_mov_b32_dpp v114, v113 quad_perm:[1,1,3,3] row_mask:0xf bank_mask:0xf bound_ctrl:1
	v_mov_b32_dpp v116, v115 quad_perm:[1,1,3,3] row_mask:0xf bank_mask:0xf bound_ctrl:1
	v_mov_b32_dpp v120, v117 quad_perm:[1,1,3,3] row_mask:0xf bank_mask:0xf bound_ctrl:1
	v_mov_b32_dpp v122, v118 quad_perm:[1,1,3,3] row_mask:0xf bank_mask:0xf bound_ctrl:1
	v_mov_b32_dpp v123, v119 quad_perm:[1,1,3,3] row_mask:0xf bank_mask:0xf bound_ctrl:1
	v_mov_b32_dpp v124, v121 quad_perm:[1,1,3,3] row_mask:0xf bank_mask:0xf bound_ctrl:1
	s_and_saveexec_b64 s[4:5], s[6:7]
	s_cbranch_execz .LBB0_730
	v_cvt_pk_bf16_f32 v93, v93, v94
	v_cvt_pk_bf16_f32 v94, v95, v96
	v_lshl_add_u32 v95, v53, 1, s14
	v_cvt_pk_bf16_f32 v101, v101, v104
	v_add_u32_e32 v96, 0x400, v95
	v_cvt_pk_bf16_f32 v102, v102, v106
	ds_write2_b32 v96, v94, v101 offset0:176 offset1:212
	v_add_u32_e32 v94, 0xe00, v95
	v_cvt_pk_bf16_f32 v118, v118, v122
	v_cvt_pk_bf16_f32 v117, v117, v120
	v_cvt_pk_bf16_f32 v109, v109, v110
	v_cvt_pk_bf16_f32 v110, v111, v112
	v_cvt_pk_bf16_f32 v105, v105, v108
	v_cvt_pk_bf16_f32 v103, v103, v107
	v_cvt_pk_bf16_f32 v99, v99, v100
	v_cvt_pk_bf16_f32 v97, v97, v98
	ds_write2_b32 v94, v93, v102 offset0:112 offset1:148
	v_add_u32_e32 v93, 0x1800, v95
	v_add_u32_e32 v94, 0x2000, v95
	v_add_u32_e32 v96, 0x600, v95
	v_add_u32_e32 v95, 0x1000, v95
	v_cvt_pk_bf16_f32 v121, v121, v124
	v_cvt_pk_bf16_f32 v119, v119, v123
	v_cvt_pk_bf16_f32 v115, v115, v116
	v_cvt_pk_bf16_f32 v113, v113, v114
	ds_write2_b32 v93, v97, v103 offset0:48 offset1:84
	ds_write2_b32 v94, v99, v105 offset0:112 offset1:148
	ds_write2_b32 v96, v110, v117 offset0:120 offset1:156
	ds_write2_b32 v95, v109, v118 offset0:56 offset1:92
	ds_write2_b32 v93, v113, v119 offset0:120 offset1:156
	ds_write2_b32 v94, v115, v121 offset0:184 offset1:220

.LBB0_738:
	s_and_b64 vcc, exec, s[4:5]
	s_cbranch_vccz .LBB0_753
	v_lshlrev_b32_e32 v5, 1, v148
	s_add_i32 s4, 0, 0x19c00
	v_add_u32_e32 v2, s4, v5
	ds_read_u16 v40, v2 offset:6656
	ds_read_u16 v41, v2 offset:6784
	ds_read_u16 v42, v2 offset:6912
	ds_read_u16 v43, v2 offset:7040
	ds_read_u16 v44, v2 offset:7168
	ds_read_u16 v45, v2 offset:7296
	ds_read_u16 v46, v2 offset:7424
	ds_read_u16 v47, v2 offset:7552
	v_add_u32_e32 v3, s4, v148
	ds_read_u16 v48, v2 offset:7680
	ds_read_u16 v49, v2 offset:7808
	ds_read_u16 v50, v2 offset:7936
	ds_read_u16 v51, v2 offset:8064
	ds_read_u8 v1, v3 offset:8768
	ds_read_u8 v9, v3 offset:8896
	ds_read_u8 v0, v3 offset:8832
	ds_read_u8 v8, v3 offset:8704
	ds_read_u16 v58, v2 offset:1024
	ds_read_u16 v12, v2 offset:3072
	ds_read_u16 v61, v2 offset:1152
	ds_read_u16 v13, v2 offset:3200
	ds_read_u16 v64, v2 offset:1280
	ds_read_u16 v14, v2 offset:3328
	ds_read_u16 v15, v2 offset:3456
	ds_read_u16 v67, v2 offset:1408
	ds_read_u16 v68, v2 offset:6144
	ds_read_u16 v69, v2 offset:6272
	ds_read_u16 v70, v2 offset:6400
	ds_read_u16 v71, v2 offset:6528
	ds_read_u16 v72, v2 offset:5120
	ds_read_u16 v74, v2 offset:5248
	ds_read_u16 v76, v2 offset:5376
	ds_read_u16 v78, v2 offset:5504
	s_add_i32 s4, 0, 0x1c480
	v_mov_b32_e32 v7, s4
	s_add_i32 s4, 0, 0x1c490
	v_mov_b32_e32 v3, s4
	s_add_i32 s4, 0, 0x1c4a0
	v_mov_b32_e32 v10, s4
	s_add_i32 s4, 0, 0x1c4b0
	v_mov_b32_e32 v11, s4
	ds_read_b32 v2, v7
	ds_read_b32 v3, v3
	ds_read_b32 v10, v10
	ds_read_b32 v11, v11
	v_and_b32_e32 v7, 1, v128
	v_lshrrev_b32_e32 v16, 1, v128
	v_cmp_eq_u32_e64 s[6:7], 0, v7
	v_and_b32_e32 v7, 50, v128
	v_and_b32_e32 v5, 8, v5
	v_and_b32_e32 v16, 4, v16
	v_or3_b32 v52, v16, v7, v5
	v_and_b32_e32 v5, 32, v128
	v_and_b32_e32 v7, 31, v128
	s_mov_b32 s13, 0
	v_mul_u32_u24_e32 v53, 0x50, v148
	v_mul_u32_u24_e32 v54, 48, v5
	v_mul_u32_u24_e32 v55, 48, v7
	v_mov_b32_e32 v5, v4
	v_mov_b32_e32 v7, v6
	s_mov_b32 s12, 0x3b808081
	s_waitcnt lgkmcnt(0)
	s_branch .LBB0_742

.LBB0_744:
	v_cndmask_b32_e64 v28, 0, 1, s[14:15]
	v_cmp_ne_u32_e64 s[8:9], 1, v28
	s_andn2_b64 vcc, exec, s[14:15]
	s_cbranch_vccnz .LBB0_748
	v_lshlrev_b32_e32 v28, 16, v68
	v_add_f32_e32 v28, 0, v28
	v_lshlrev_b32_e32 v29, 16, v69
	v_add_f32_e32 v28, v28, v29
	v_lshlrev_b32_e32 v29, 16, v70
	v_add_f32_e32 v28, v28, v29
	v_lshlrev_b32_e32 v29, 16, v71
	v_add_f32_e32 v28, v28, v29
	v_lshlrev_b32_e32 v29, 16, v40
	v_add_f32_e32 v28, v28, v29
	v_lshlrev_b32_e32 v29, 16, v41
	v_add_f32_e32 v28, v28, v29
	v_lshlrev_b32_e32 v29, 16, v42
	v_add_f32_e32 v28, v28, v29
	v_lshlrev_b32_e32 v29, 16, v43
	v_add_f32_e32 v28, v28, v29
	v_lshlrev_b32_e32 v29, 16, v44
	v_add_f32_e32 v29, v28, v29
	v_exp_f32_e32 v39, v28
	v_lshlrev_b32_e32 v30, 16, v45
	v_lshlrev_b32_e32 v33, 16, v13
	v_exp_f32_e32 v101, v29
	v_lshlrev_b32_e32 v32, 16, v12
	v_cvt_f32_u32_e32 v35, v1
	v_cvt_f32_u32_e32 v34, v8
	v_add_f32_e32 v38, v29, v30
	v_lshlrev_b32_e32 v30, 16, v46
	v_pk_mul_f32 v[36:37], v[4:5], v[32:33]
	v_cvt_f32_u32_e32 v117, v9
	v_cvt_f32_u32_e32 v116, v0
	v_add_f32_e32 v109, v38, v30
	v_lshlrev_b32_e32 v30, 16, v47
	v_pk_mul_f32 v[36:37], v[36:37], v[2:3]
	v_exp_f32_e32 v111, v38
	v_add_f32_e32 v92, v109, v30
	v_lshlrev_b32_e32 v30, 16, v58
	v_mul_f32_e32 v95, v39, v36
	v_lshlrev_b32_e32 v39, 16, v15
	v_lshlrev_b32_e32 v38, 16, v14
	v_mul_f32_e32 v93, v101, v30
	v_pk_mul_f32 v[30:31], v[34:35], s[12:13] op_sel_hi:[1,0]
	v_pk_mul_f32 v[112:113], v[4:5], v[38:39]
	v_rcp_f32_e32 v28, v101
	v_lshlrev_b32_e32 v102, 16, v61
	v_pk_mul_f32 v[30:31], v[30:31], v[36:37]
	v_mul_f32_e32 v101, v101, v37
	v_pk_mul_f32 v[36:37], v[116:117], s[12:13] op_sel_hi:[1,0]
	v_pk_mul_f32 v[118:119], v[112:113], v[10:11]
	v_rcp_f32_e32 v29, v111
	v_mul_f32_e32 v102, v111, v102
	v_exp_f32_e32 v120, v109
	v_mul_f32_e32 v111, v111, v118
	v_pk_mul_f32 v[36:37], v[36:37], v[118:119]
	v_exp_f32_e32 v118, v92
	v_pk_fma_f32 v[34:35], v[34:35], s[12:13], -1.0 op_sel_hi:[1,0,0]
	v_pk_fma_f32 v[116:117], v[116:117], s[12:13], -1.0 op_sel_hi:[1,0,0]
	v_pk_fma_f32 v[34:35], v[6:7], v[34:35], 1.0 op_sel_hi:[1,1,0]
	v_pk_fma_f32 v[116:117], v[6:7], v[116:117], 1.0 op_sel_hi:[1,1,0]
	v_pk_mul_f32 v[32:33], v[34:35], v[32:33]
	v_lshlrev_b32_e32 v35, 16, v64
	v_rcp_f32_e32 v34, v120
	v_mul_f32_e32 v109, v120, v35
	v_rcp_f32_e32 v35, v118
	s_and_b32 s4, s13, 2
	v_lshlrev_b32_e32 v121, 16, v67
	v_pk_mul_f32 v[38:39], v[116:117], v[38:39]
	s_mulk_i32 s4, 0x5f00
	v_mul_f32_e32 v97, v28, v30
	v_mul_f32_e32 v99, v28, v32
	v_mul_f32_e32 v103, v29, v31
	v_mul_f32_e32 v105, v29, v33
	v_mul_f32_e32 v113, v34, v36
	v_mul_f32_e32 v115, v34, v38
	v_mul_f32_e32 v117, v120, v119
	v_mul_f32_e32 v118, v118, v121
	v_mul_f32_e32 v119, v35, v37
	v_mul_f32_e32 v121, v35, v39
	s_add_i32 s14, s4, 0
	v_mov_b32_dpp v94, v93 quad_perm:[1,1,3,3] row_mask:0xf bank_mask:0xf bound_ctrl:1
	v_mov_b32_dpp v96, v95 quad_perm:[1,1,3,3] row_mask:0xf bank_mask:0xf bound_ctrl:1
	v_mov_b32_dpp v98, v97 quad_perm:[1,1,3,3] row_mask:0xf bank_mask:0xf bound_ctrl:1
	v_mov_b32_dpp v100, v99 quad_perm:[1,1,3,3] row_mask:0xf bank_mask:0xf bound_ctrl:1
	v_mov_b32_dpp v104, v101 quad_perm:[1,1,3,3] row_mask:0xf bank_mask:0xf bound_ctrl:1
	v_mov_b32_dpp v106, v102 quad_perm:[1,1,3,3] row_mask:0xf bank_mask:0xf bound_ctrl:1
	v_mov_b32_dpp v107, v103 quad_perm:[1,1,3,3] row_mask:0xf bank_mask:0xf bound_ctrl:1
	v_mov_b32_dpp v108, v105 quad_perm:[1,1,3,3] row_mask:0xf bank_mask:0xf bound_ctrl:1
	v_mov_b32_dpp v110, v109 quad_perm:[1,1,3,3] row_mask:0xf bank_mask:0xf bound_ctrl:1
	v_mov_b32_dpp v112, v111 quad_perm:[1,1,3,3] row_mask:0xf bank_mask:0xf bound_ctrl:1
	v_mov_b32_dpp v114, v113 quad_perm:[1,1,3,3] row_mask:0xf bank_mask:0xf bound_ctrl:1
	v_mov_b32_dpp v116, v115 quad_perm:[1,1,3,3] row_mask:0xf bank_mask:0xf bound_ctrl:1
	v_mov_b32_dpp v120, v117 quad_perm:[1,1,3,3] row_mask:0xf bank_mask:0xf bound_ctrl:1
	v_mov_b32_dpp v122, v118 quad_perm:[1,1,3,3] row_mask:0xf bank_mask:0xf bound_ctrl:1
	v_mov_b32_dpp v123, v119 quad_perm:[1,1,3,3] row_mask:0xf bank_mask:0xf bound_ctrl:1
	v_mov_b32_dpp v124, v121 quad_perm:[1,1,3,3] row_mask:0xf bank_mask:0xf bound_ctrl:1
	s_and_saveexec_b64 s[4:5], s[6:7]
	s_cbranch_execz .LBB0_747
	v_cvt_pk_bf16_f32 v93, v93, v94
	v_cvt_pk_bf16_f32 v94, v95, v96
	v_lshl_add_u32 v95, v52, 1, s14
	v_cvt_pk_bf16_f32 v101, v101, v104
	v_add_u32_e32 v96, 0x400, v95
	v_cvt_pk_bf16_f32 v102, v102, v106
	ds_write2_b32 v96, v94, v101 offset0:32 offset1:68
	v_add_u32_e32 v94, 0xc00, v95
	v_cvt_pk_bf16_f32 v103, v103, v107
	v_cvt_pk_bf16_f32 v97, v97, v98
	ds_write2_b32 v94, v93, v102 offset0:96 offset1:132
	v_add_u32_e32 v93, 0x1400, v95
	v_cvt_pk_bf16_f32 v105, v105, v108
	v_cvt_pk_bf16_f32 v99, v99, v100
	ds_write2_b32 v93, v97, v103 offset0:160 offset1:196
	v_add_u32_e32 v93, 0x1e00, v95
	v_cvt_pk_bf16_f32 v119, v119, v123
	v_cvt_pk_bf16_f32 v118, v118, v122
	v_cvt_pk_bf16_f32 v117, v117, v120
	v_cvt_pk_bf16_f32 v113, v113, v114
	v_cvt_pk_bf16_f32 v109, v109, v110
	v_cvt_pk_bf16_f32 v110, v111, v112
	ds_write2_b32 v93, v99, v105 offset0:96 offset1:132
	ds_write2_b32 v96, v110, v117 offset0:104 offset1:140
	ds_write2_b32 v94, v109, v118 offset0:168 offset1:204
	v_add_u32_e32 v93, 0x1600, v95
	v_cvt_pk_bf16_f32 v121, v121, v124
	v_cvt_pk_bf16_f32 v115, v115, v116
	ds_write2_b32 v93, v113, v119 offset0:104 offset1:140
	v_add_u32_e32 v93, 0x2000, v95
	ds_write2_b32 v93, v115, v121 offset0:40 offset1:76

.LBB0_754:
	s_and_b64 vcc, exec, s[4:5]
	s_cbranch_vccz .LBB0_769
	v_lshlrev_b32_e32 v5, 1, v148
	s_add_i32 s4, 0, 0x19c00
	v_add_u32_e32 v2, s4, v5
	ds_read_u16 v40, v2 offset:6656
	ds_read_u16 v41, v2 offset:6784
	ds_read_u16 v42, v2 offset:6912
	ds_read_u16 v43, v2 offset:7040
	ds_read_u16 v44, v2 offset:7168
	ds_read_u16 v45, v2 offset:7296
	ds_read_u16 v46, v2 offset:7424
	ds_read_u16 v47, v2 offset:7552
	v_add_u32_e32 v3, s4, v148
	ds_read_u16 v48, v2 offset:7680
	ds_read_u16 v49, v2 offset:7808
	ds_read_u16 v50, v2 offset:7936
	ds_read_u16 v51, v2 offset:8064
	ds_read_u8 v1, v3 offset:8512
	ds_read_u8 v9, v3 offset:8640
	ds_read_u8 v0, v3 offset:8576
	ds_read_u8 v8, v3 offset:8448
	ds_read_u16 v58, v2 offset:512
	ds_read_u16 v12, v2 offset:2560
	ds_read_u16 v61, v2 offset:640
	ds_read_u16 v13, v2 offset:2688
	ds_read_u16 v64, v2 offset:768
	ds_read_u16 v14, v2 offset:2816
	ds_read_u16 v15, v2 offset:2944
	ds_read_u16 v67, v2 offset:896
	ds_read_u16 v68, v2 offset:6144
	ds_read_u16 v69, v2 offset:6272
	ds_read_u16 v70, v2 offset:6400
	ds_read_u16 v71, v2 offset:6528
	ds_read_u16 v72, v2 offset:4608
	ds_read_u16 v74, v2 offset:4736
	ds_read_u16 v76, v2 offset:4864
	ds_read_u16 v78, v2 offset:4992
	s_add_i32 s4, 0, 0x1c440
	v_mov_b32_e32 v7, s4
	s_add_i32 s4, 0, 0x1c450
	v_mov_b32_e32 v3, s4
	s_add_i32 s4, 0, 0x1c460
	v_mov_b32_e32 v10, s4
	s_add_i32 s4, 0, 0x1c470
	v_mov_b32_e32 v11, s4
	ds_read_b32 v2, v7
	ds_read_b32 v3, v3
	ds_read_b32 v10, v10
	ds_read_b32 v11, v11
	v_and_b32_e32 v7, 1, v128
	v_lshrrev_b32_e32 v16, 1, v128
	v_cmp_eq_u32_e64 s[6:7], 0, v7
	v_and_b32_e32 v7, 50, v128
	v_and_b32_e32 v5, 8, v5
	v_and_b32_e32 v16, 4, v16
	v_or3_b32 v52, v16, v7, v5
	v_and_b32_e32 v5, 32, v128
	v_and_b32_e32 v7, 31, v128
	s_mov_b32 s13, 0
	v_mul_u32_u24_e32 v53, 0x50, v148
	v_mul_u32_u24_e32 v54, 48, v5
	v_mul_u32_u24_e32 v55, 48, v7
	v_mov_b32_e32 v5, v4
	v_mov_b32_e32 v7, v6
	s_mov_b32 s12, 0x3b808081
	s_waitcnt lgkmcnt(0)
	s_branch .LBB0_758

.LBB0_760:
	v_cndmask_b32_e64 v28, 0, 1, s[14:15]
	v_cmp_ne_u32_e64 s[8:9], 1, v28
	s_andn2_b64 vcc, exec, s[14:15]
	s_cbranch_vccnz .LBB0_764
	v_lshlrev_b32_e32 v28, 16, v68
	v_add_f32_e32 v28, 0, v28
	v_lshlrev_b32_e32 v29, 16, v69
	v_add_f32_e32 v28, v28, v29
	v_lshlrev_b32_e32 v29, 16, v70
	v_add_f32_e32 v28, v28, v29
	v_lshlrev_b32_e32 v29, 16, v71
	v_add_f32_e32 v28, v28, v29
	v_lshlrev_b32_e32 v29, 16, v40
	v_add_f32_e32 v29, v28, v29
	v_exp_f32_e32 v39, v28
	v_lshlrev_b32_e32 v30, 16, v41
	v_lshlrev_b32_e32 v33, 16, v13
	v_exp_f32_e32 v101, v29
	v_lshlrev_b32_e32 v32, 16, v12
	v_cvt_f32_u32_e32 v35, v1
	v_cvt_f32_u32_e32 v34, v8
	v_add_f32_e32 v38, v29, v30
	v_lshlrev_b32_e32 v30, 16, v42
	v_pk_mul_f32 v[36:37], v[4:5], v[32:33]
	v_cvt_f32_u32_e32 v117, v9
	v_cvt_f32_u32_e32 v116, v0
	v_add_f32_e32 v109, v38, v30
	v_lshlrev_b32_e32 v30, 16, v43
	v_pk_mul_f32 v[36:37], v[36:37], v[2:3]
	v_exp_f32_e32 v111, v38
	v_add_f32_e32 v92, v109, v30
	v_lshlrev_b32_e32 v30, 16, v58
	v_mul_f32_e32 v95, v39, v36
	v_lshlrev_b32_e32 v39, 16, v15
	v_lshlrev_b32_e32 v38, 16, v14
	v_mul_f32_e32 v93, v101, v30
	v_pk_mul_f32 v[30:31], v[34:35], s[12:13] op_sel_hi:[1,0]
	v_pk_mul_f32 v[112:113], v[4:5], v[38:39]
	v_rcp_f32_e32 v28, v101
	v_lshlrev_b32_e32 v102, 16, v61
	v_pk_mul_f32 v[30:31], v[30:31], v[36:37]
	v_mul_f32_e32 v101, v101, v37
	v_pk_mul_f32 v[36:37], v[116:117], s[12:13] op_sel_hi:[1,0]
	v_pk_mul_f32 v[118:119], v[112:113], v[10:11]
	v_rcp_f32_e32 v29, v111
	v_mul_f32_e32 v102, v111, v102
	v_exp_f32_e32 v120, v109
	v_mul_f32_e32 v111, v111, v118
	v_pk_mul_f32 v[36:37], v[36:37], v[118:119]
	v_exp_f32_e32 v118, v92
	v_pk_fma_f32 v[34:35], v[34:35], s[12:13], -1.0 op_sel_hi:[1,0,0]
	v_pk_fma_f32 v[116:117], v[116:117], s[12:13], -1.0 op_sel_hi:[1,0,0]
	v_pk_fma_f32 v[34:35], v[6:7], v[34:35], 1.0 op_sel_hi:[1,1,0]
	v_pk_fma_f32 v[116:117], v[6:7], v[116:117], 1.0 op_sel_hi:[1,1,0]
	v_pk_mul_f32 v[32:33], v[34:35], v[32:33]
	v_lshlrev_b32_e32 v35, 16, v64
	v_rcp_f32_e32 v34, v120
	v_mul_f32_e32 v109, v120, v35
	v_rcp_f32_e32 v35, v118
	s_and_b32 s4, s13, 2
	v_lshlrev_b32_e32 v121, 16, v67
	v_pk_mul_f32 v[38:39], v[116:117], v[38:39]
	s_mulk_i32 s4, 0x5f00
	v_mul_f32_e32 v97, v28, v30
	v_mul_f32_e32 v99, v28, v32
	v_mul_f32_e32 v103, v29, v31
	v_mul_f32_e32 v105, v29, v33
	v_mul_f32_e32 v113, v34, v36
	v_mul_f32_e32 v115, v34, v38
	v_mul_f32_e32 v117, v120, v119
	v_mul_f32_e32 v118, v118, v121
	v_mul_f32_e32 v119, v35, v37
	v_mul_f32_e32 v121, v35, v39
	s_add_i32 s14, s4, 0
	v_mov_b32_dpp v94, v93 quad_perm:[1,1,3,3] row_mask:0xf bank_mask:0xf bound_ctrl:1
	v_mov_b32_dpp v96, v95 quad_perm:[1,1,3,3] row_mask:0xf bank_mask:0xf bound_ctrl:1
	v_mov_b32_dpp v98, v97 quad_perm:[1,1,3,3] row_mask:0xf bank_mask:0xf bound_ctrl:1
	v_mov_b32_dpp v100, v99 quad_perm:[1,1,3,3] row_mask:0xf bank_mask:0xf bound_ctrl:1
	v_mov_b32_dpp v104, v101 quad_perm:[1,1,3,3] row_mask:0xf bank_mask:0xf bound_ctrl:1
	v_mov_b32_dpp v106, v102 quad_perm:[1,1,3,3] row_mask:0xf bank_mask:0xf bound_ctrl:1
	v_mov_b32_dpp v107, v103 quad_perm:[1,1,3,3] row_mask:0xf bank_mask:0xf bound_ctrl:1
	v_mov_b32_dpp v108, v105 quad_perm:[1,1,3,3] row_mask:0xf bank_mask:0xf bound_ctrl:1
	v_mov_b32_dpp v110, v109 quad_perm:[1,1,3,3] row_mask:0xf bank_mask:0xf bound_ctrl:1
	v_mov_b32_dpp v112, v111 quad_perm:[1,1,3,3] row_mask:0xf bank_mask:0xf bound_ctrl:1
	v_mov_b32_dpp v114, v113 quad_perm:[1,1,3,3] row_mask:0xf bank_mask:0xf bound_ctrl:1
	v_mov_b32_dpp v116, v115 quad_perm:[1,1,3,3] row_mask:0xf bank_mask:0xf bound_ctrl:1
	v_mov_b32_dpp v120, v117 quad_perm:[1,1,3,3] row_mask:0xf bank_mask:0xf bound_ctrl:1
	v_mov_b32_dpp v122, v118 quad_perm:[1,1,3,3] row_mask:0xf bank_mask:0xf bound_ctrl:1
	v_mov_b32_dpp v123, v119 quad_perm:[1,1,3,3] row_mask:0xf bank_mask:0xf bound_ctrl:1
	v_mov_b32_dpp v124, v121 quad_perm:[1,1,3,3] row_mask:0xf bank_mask:0xf bound_ctrl:1
	s_and_saveexec_b64 s[4:5], s[6:7]
	s_cbranch_execz .LBB0_763
	v_cvt_pk_bf16_f32 v101, v101, v104
	v_cvt_pk_bf16_f32 v93, v93, v94
	v_cvt_pk_bf16_f32 v94, v95, v96
	v_lshl_add_u32 v95, v52, 1, s14
	v_cvt_pk_bf16_f32 v102, v102, v106
	ds_write2_b32 v95, v94, v101 offset0:144 offset1:180
	v_add_u32_e32 v94, 0x800, v95
	v_cvt_pk_bf16_f32 v105, v105, v108
	v_cvt_pk_bf16_f32 v103, v103, v107
	v_cvt_pk_bf16_f32 v99, v99, v100
	v_cvt_pk_bf16_f32 v97, v97, v98
	ds_write2_b32 v94, v93, v102 offset0:208 offset1:244
	v_add_u32_e32 v93, 0x1400, v95
	v_add_u32_e32 v94, 0x1c00, v95
	v_cvt_pk_bf16_f32 v118, v118, v122
	v_cvt_pk_bf16_f32 v117, v117, v120
	v_cvt_pk_bf16_f32 v109, v109, v110
	v_cvt_pk_bf16_f32 v110, v111, v112
	ds_write2_b32 v93, v97, v103 offset0:16 offset1:52
	ds_write2_b32 v94, v99, v105 offset0:80 offset1:116
	ds_write2_b32 v95, v110, v117 offset0:216 offset1:252
	v_add_u32_e32 v95, 0xc00, v95
	v_cvt_pk_bf16_f32 v121, v121, v124
	v_cvt_pk_bf16_f32 v119, v119, v123
	v_cvt_pk_bf16_f32 v115, v115, v116
	v_cvt_pk_bf16_f32 v113, v113, v114
	ds_write2_b32 v95, v109, v118 offset0:24 offset1:60
	ds_write2_b32 v93, v113, v119 offset0:88 offset1:124
	ds_write2_b32 v94, v115, v121 offset0:152 offset1:188

.LBB0_770:
	s_and_b64 vcc, exec, s[4:5]
	s_cbranch_vccz .LBB0_812
	s_cmp_gt_i32 s70, 2
	s_mov_b64 s[4:5], -1
	s_cbranch_scc0 .LBB0_810
	s_cmp_gt_i32 s70, 3
	v_and_b32_e32 v42, 3, v128
	s_cbranch_scc0 .LBB0_788
	s_add_i32 s4, 0, 0x19c00
	v_lshl_add_u32 v2, v148, 1, s4
	ds_read_u16 v43, v2 offset:6656
	ds_read_u16 v44, v2 offset:6784
	ds_read_u16 v45, v2 offset:6912
	ds_read_u16 v46, v2 offset:7040
	ds_read_u16 v47, v2 offset:7168
	ds_read_u16 v48, v2 offset:7296
	ds_read_u16 v49, v2 offset:7424
	ds_read_u16 v50, v2 offset:7552
	v_add_u32_e32 v3, s4, v148
	ds_read_u16 v51, v2 offset:7680
	ds_read_u16 v52, v2 offset:7808
	ds_read_u16 v53, v2 offset:7936
	ds_read_u16 v54, v2 offset:8064
	ds_read_u8 v1, v3 offset:8256
	ds_read_u8 v9, v3 offset:8384
	ds_read_u8 v0, v3 offset:8320
	ds_read_u8 v8, v3 offset:8192
	ds_read_u16 v63, v2
	ds_read_u16 v12, v2 offset:2048
	ds_read_u16 v66, v2 offset:128
	ds_read_u16 v13, v2 offset:2176
	ds_read_u16 v69, v2 offset:256
	ds_read_u16 v14, v2 offset:2304
	ds_read_u16 v15, v2 offset:2432
	ds_read_u16 v73, v2 offset:384
	ds_read_u16 v74, v2 offset:6144
	ds_read_u16 v75, v2 offset:6272
	ds_read_u16 v76, v2 offset:6400
	ds_read_u16 v77, v2 offset:6528
	ds_read_u16 v78, v2 offset:4096
	ds_read_u16 v79, v2 offset:4224
	ds_read_u16 v80, v2 offset:4352
	ds_read_u16 v82, v2 offset:4480
	s_add_i32 s4, 0, 0x1c400
	v_mov_b32_e32 v5, s4
	s_add_i32 s4, 0, 0x1c410
	v_mov_b32_e32 v3, s4
	s_add_i32 s4, 0, 0x1c420
	v_mov_b32_e32 v7, s4
	s_add_i32 s4, 0, 0x1c430
	v_mov_b32_e32 v11, s4
	ds_read_b32 v2, v5
	ds_read_b32 v3, v3
	ds_read_b32 v10, v7
	ds_read_b32 v11, v11
	v_and_b32_e32 v16, 1, v128
	v_bfe_u32 v5, v128, 2, 1
	v_lshrrev_b32_e32 v7, 1, v148
	v_cmp_eq_u32_e64 s[6:7], 0, v16
	v_and_b32_e32 v16, 48, v128
	v_and_or_b32 v55, v7, 12, v42
	v_lshl_or_b32 v16, v5, 3, v16
	v_and_or_b32 v56, v55, 6, v16
	v_and_b32_e32 v16, 31, v128
	v_and_b32_e32 v17, 32, v128
	s_mov_b32 s11, 0
	v_mul_u32_u24_e32 v57, 0x50, v148
	v_mul_u32_u24_e32 v58, 48, v17
	v_mul_u32_u24_e32 v59, 48, v16
	v_and_b32_e32 v60, 16, v7
	v_lshlrev_b32_e32 v61, 7, v5
	v_mov_b32_e32 v5, v4
	v_mov_b32_e32 v7, v6
	s_mov_b32 s10, 0x3b808081
	s_waitcnt lgkmcnt(0)
	s_branch .LBB0_776

.LBB0_778:
	v_cndmask_b32_e64 v28, 0, 1, s[12:13]
	v_cmp_ne_u32_e64 s[8:9], 1, v28
	s_andn2_b64 vcc, exec, s[12:13]
	s_cbranch_vccnz .LBB0_782
	v_lshlrev_b32_e32 v28, 16, v74
	v_add_f32_e32 v28, 0, v28
	v_lshlrev_b32_e32 v29, 16, v75
	v_exp_f32_e32 v41, v28
	v_cvt_f32_u32_e32 v35, v1
	v_cvt_f32_u32_e32 v34, v8
	v_add_f32_e32 v29, v28, v29
	v_lshlrev_b32_e32 v30, 16, v76
	v_add_f32_e32 v40, v29, v30
	v_lshlrev_b32_e32 v30, 16, v77
	v_lshlrev_b32_e32 v33, 16, v13
	v_lshlrev_b32_e32 v32, 16, v12
	v_add_f32_e32 v98, v40, v30
	v_lshlrev_b32_e32 v30, 16, v63
	v_pk_mul_f32 v[36:37], v[4:5], v[32:33]
	v_cvt_f32_u32_e32 v121, v9
	v_cvt_f32_u32_e32 v120, v0
	v_mul_f32_e32 v99, v41, v30
	v_pk_mul_f32 v[30:31], v[34:35], s[10:11] op_sel_hi:[1,0]
	v_pk_mul_f32 v[38:39], v[36:37], v[2:3]
	v_exp_f32_e32 v115, v29
	v_rcp_f32_e32 v28, v41
	v_pk_mul_f32 v[30:31], v[30:31], v[38:39]
	v_mul_f32_e32 v39, v41, v39
	v_lshlrev_b32_e32 v41, 16, v15
	v_exp_f32_e32 v124, v40
	v_lshlrev_b32_e32 v40, 16, v14
	v_pk_mul_f32 v[116:117], v[4:5], v[40:41]
	v_lshlrev_b32_e32 v106, 16, v66
	v_pk_mul_f32 v[36:37], v[120:121], s[10:11] op_sel_hi:[1,0]
	v_pk_mul_f32 v[122:123], v[116:117], v[10:11]
	v_rcp_f32_e32 v29, v115
	v_mul_f32_e32 v106, v115, v106
	v_mul_f32_e32 v115, v115, v122
	v_pk_mul_f32 v[36:37], v[36:37], v[122:123]
	v_exp_f32_e32 v122, v98
	v_pk_fma_f32 v[34:35], v[34:35], s[10:11], -1.0 op_sel_hi:[1,0,0]
	v_pk_fma_f32 v[120:121], v[120:121], s[10:11], -1.0 op_sel_hi:[1,0,0]
	v_pk_fma_f32 v[34:35], v[6:7], v[34:35], 1.0 op_sel_hi:[1,1,0]
	v_pk_fma_f32 v[120:121], v[6:7], v[120:121], 1.0 op_sel_hi:[1,1,0]
	v_pk_mul_f32 v[32:33], v[34:35], v[32:33]
	v_lshlrev_b32_e32 v35, 16, v69
	v_rcp_f32_e32 v34, v124
	v_mul_f32_e32 v113, v124, v35
	v_rcp_f32_e32 v35, v122
	s_and_b32 s4, s11, 2
	v_lshlrev_b32_e32 v125, 16, v73
	v_pk_mul_f32 v[40:41], v[120:121], v[40:41]
	s_mulk_i32 s4, 0x5f00
	v_mul_f32_e32 v102, v28, v30
	v_mul_f32_e32 v104, v28, v32
	v_mul_f32_e32 v107, v29, v31
	v_mul_f32_e32 v109, v29, v33
	v_mul_f32_e32 v117, v34, v36
	v_mul_f32_e32 v119, v34, v40
	v_mul_f32_e32 v121, v124, v123
	v_mul_f32_e32 v122, v122, v125
	v_mul_f32_e32 v123, v35, v37
	v_mul_f32_e32 v125, v35, v41
	s_add_i32 s12, s4, 0
	v_mov_b32_dpp v100, v99 quad_perm:[1,1,3,3] row_mask:0xf bank_mask:0xf bound_ctrl:1
	v_mov_b32_dpp v101, v38 quad_perm:[1,1,3,3] row_mask:0xf bank_mask:0xf bound_ctrl:1
	v_mov_b32_dpp v103, v102 quad_perm:[1,1,3,3] row_mask:0xf bank_mask:0xf bound_ctrl:1
	v_mov_b32_dpp v105, v104 quad_perm:[1,1,3,3] row_mask:0xf bank_mask:0xf bound_ctrl:1
	v_mov_b32_dpp v108, v39 quad_perm:[1,1,3,3] row_mask:0xf bank_mask:0xf bound_ctrl:1
	v_mov_b32_dpp v110, v106 quad_perm:[1,1,3,3] row_mask:0xf bank_mask:0xf bound_ctrl:1
	v_mov_b32_dpp v111, v107 quad_perm:[1,1,3,3] row_mask:0xf bank_mask:0xf bound_ctrl:1
	v_mov_b32_dpp v112, v109 quad_perm:[1,1,3,3] row_mask:0xf bank_mask:0xf bound_ctrl:1
	v_mov_b32_dpp v114, v113 quad_perm:[1,1,3,3] row_mask:0xf bank_mask:0xf bound_ctrl:1
	v_mov_b32_dpp v116, v115 quad_perm:[1,1,3,3] row_mask:0xf bank_mask:0xf bound_ctrl:1
	v_mov_b32_dpp v118, v117 quad_perm:[1,1,3,3] row_mask:0xf bank_mask:0xf bound_ctrl:1
	v_mov_b32_dpp v120, v119 quad_perm:[1,1,3,3] row_mask:0xf bank_mask:0xf bound_ctrl:1
	v_mov_b32_dpp v124, v121 quad_perm:[1,1,3,3] row_mask:0xf bank_mask:0xf bound_ctrl:1
	v_mov_b32_dpp v126, v122 quad_perm:[1,1,3,3] row_mask:0xf bank_mask:0xf bound_ctrl:1
	v_mov_b32_dpp v127, v123 quad_perm:[1,1,3,3] row_mask:0xf bank_mask:0xf bound_ctrl:1
	v_mov_b32_dpp v129, v125 quad_perm:[1,1,3,3] row_mask:0xf bank_mask:0xf bound_ctrl:1
	s_and_saveexec_b64 s[4:5], s[6:7]
	s_cbranch_execz .LBB0_781
	v_cvt_pk_bf16_f32 v39, v39, v108
	v_cvt_pk_bf16_f32 v99, v99, v100
	v_cvt_pk_bf16_f32 v38, v38, v101
	v_lshl_add_u32 v100, v56, 1, s12
	v_cvt_pk_bf16_f32 v106, v106, v110
	ds_write2_b32 v100, v38, v39 offset1:36
	v_add_u32_e32 v38, 0x800, v100
	v_cvt_pk_bf16_f32 v109, v109, v112
	v_cvt_pk_bf16_f32 v107, v107, v111
	v_cvt_pk_bf16_f32 v104, v104, v105
	v_cvt_pk_bf16_f32 v102, v102, v103
	ds_write2_b32 v38, v99, v106 offset0:64 offset1:100
	v_add_u32_e32 v39, 0x1000, v100
	v_add_u32_e32 v99, 0x1800, v100
	v_cvt_pk_bf16_f32 v125, v125, v129
	v_cvt_pk_bf16_f32 v123, v123, v127
	v_cvt_pk_bf16_f32 v122, v122, v126
	v_cvt_pk_bf16_f32 v121, v121, v124
	v_cvt_pk_bf16_f32 v119, v119, v120
	v_cvt_pk_bf16_f32 v117, v117, v118
	v_cvt_pk_bf16_f32 v113, v113, v114
	v_cvt_pk_bf16_f32 v114, v115, v116
	ds_write2_b32 v39, v102, v107 offset0:128 offset1:164
	ds_write2_b32 v99, v104, v109 offset0:192 offset1:228
	ds_write2_b32 v100, v114, v121 offset0:72 offset1:108
	ds_write2_b32 v38, v113, v122 offset0:136 offset1:172
	ds_write2_b32 v39, v117, v123 offset0:200 offset1:236
	v_add_u32_e32 v38, 0x1c00, v100
	ds_write2_b32 v38, v119, v125 offset0:8 offset1:44

.LBB0_845:
	s_cmpk_gt_u32 s4, 0x1ff
	s_cbranch_scc1 .LBB0_844
	s_and_saveexec_b64 s[0:1], vcc
	s_cbranch_execz .LBB0_843
	s_and_b32 s5, s4, 3
	s_mulk_i32 s5, 0x5f00
	s_add_i32 s5, s5, 0
	v_mov_b32_e32 v19, s5
	ds_read_b64 v[20:21], v19 offset:23104
	ds_read_b64 v[22:23], v19 offset:23168
	ds_read_b128 v[24:27], v19 offset:23232
	ds_read_b128 v[28:31], v19 offset:23296
	ds_read_b128 v[32:35], v19 offset:23360
	ds_read_b64 v[36:37], v19 offset:23376
	ds_read_b128 v[38:41], v19 offset:23424
	ds_read_b64 v[42:43], v19 offset:23440
	ds_read_b128 v[44:47], v19 offset:23488
	ds_read_b128 v[48:51], v19 offset:23504
	ds_read_b128 v[52:55], v19 offset:23552
	ds_read_b128 v[56:59], v19 offset:23568
	ds_read_b128 v[60:63], v19 offset:23616
	ds_read_b128 v[64:67], v19 offset:23632
	ds_read_b64 v[68:69], v19 offset:23648
	ds_read_b128 v[70:73], v19 offset:23680
	ds_read_b128 v[74:77], v19 offset:23696
	ds_read_b64 v[78:79], v19 offset:23712
	ds_read_b128 v[80:83], v19 offset:23744
	ds_read_b128 v[84:87], v19 offset:23760
	ds_read_b128 v[88:91], v19 offset:23776
	ds_read_b128 v[92:95], v19 offset:23808
	ds_read_b128 v[96:99], v19 offset:23824
	ds_read_b128 v[100:103], v19 offset:23840
	ds_read_b128 v[104:107], v19 offset:23872
	ds_read_b128 v[108:111], v19 offset:23888
	ds_read_b128 v[112:115], v19 offset:23904
	ds_read_b64 v[116:117], v19 offset:23920
	ds_read_b128 v[118:121], v19 offset:23936
	ds_read_b128 v[122:125], v19 offset:23952
	ds_read_b128 v[126:129], v19 offset:23968
	ds_read_b64 v[130:131], v19 offset:23984
	ds_read_b128 v[132:135], v19 offset:24000
	ds_read_b128 v[136:139], v19 offset:24016
	ds_read_b128 v[140:143], v19 offset:24032
	ds_read_b128 v[144:147], v19 offset:24048
	s_waitcnt lgkmcnt(15)
	v_fma_f32 v19, -v0, v20, v1
	v_fma_f32 v20, -v23, v19, 0
	v_fma_f32 v21, -v0, v22, v2
	v_add_f32_e32 v20, v21, v20
	v_fma_f32 v21, -v0, v24, v3
	v_fma_f32 v21, -v26, v20, v21
	v_fma_f32 v22, -v19, v25, 0
	v_add_f32_e32 v21, v22, v21
	v_fma_f32 v22, -v19, v29, 0
	v_fma_f32 v23, -v0, v28, v4
	v_fma_f32 v22, -v31, v21, v22
	v_fma_f32 v23, -v30, v20, v23
	v_fma_f32 v24, -v0, v32, v5
	v_add_f32_e32 v22, v23, v22
	v_fma_f32 v23, -v19, v33, 0
	v_fma_f32 v24, -v34, v20, v24
	v_fma_f32 v23, -v35, v21, v23
	v_fma_f32 v24, -v36, v22, v24
	v_add_f32_e32 v23, v23, v24
	v_fma_f32 v24, -v19, v39, 0
	v_fma_f32 v25, -v0, v38, v6
	v_fma_f32 v24, -v41, v21, v24
	v_fma_f32 v25, -v20, v40, v25
	v_fma_f32 v24, -v43, v23, v24
	v_fma_f32 v25, -v42, v22, v25
	v_add_f32_e32 v24, v25, v24
	v_fma_f32 v25, -v0, v44, v7
	v_fma_f32 v25, -v20, v46, v25
	v_fma_f32 v26, -v19, v45, 0
	v_fma_f32 v25, -v48, v22, v25
	v_fma_f32 v26, -v21, v47, v26
	v_fma_f32 v25, -v50, v24, v25
	v_fma_f32 v26, -v49, v23, v26
	v_add_f32_e32 v25, v26, v25
	v_fma_f32 v26, -v19, v53, 0
	v_fma_f32 v27, -v0, v52, v8
	v_fma_f32 v26, -v21, v55, v26
	v_fma_f32 v27, -v20, v54, v27
	v_fma_f32 v26, -v57, v23, v26
	v_fma_f32 v27, -v22, v56, v27
	v_fma_f32 v26, -v59, v25, v26
	v_fma_f32 v27, -v58, v24, v27
	v_fma_f32 v28, -v0, v60, v9
	v_add_f32_e32 v26, v27, v26
	v_fma_f32 v27, -v19, v61, 0
	v_fma_f32 v28, -v20, v62, v28
	v_fma_f32 v27, -v21, v63, v27
	v_fma_f32 v28, -v22, v64, v28
	v_fma_f32 v27, -v65, v23, v27
	v_fma_f32 v28, -v66, v24, v28
	v_fma_f32 v27, -v67, v25, v27
	v_fma_f32 v28, -v68, v26, v28
	v_add_f32_e32 v27, v27, v28
	v_fma_f32 v28, -v19, v71, 0
	v_fma_f32 v29, -v0, v70, v10
	v_fma_f32 v28, -v21, v73, v28
	v_fma_f32 v29, -v20, v72, v29
	v_fma_f32 v28, -v23, v75, v28
	v_fma_f32 v29, -v22, v74, v29
	v_fma_f32 v28, -v77, v25, v28
	v_fma_f32 v29, -v76, v24, v29
	v_fma_f32 v28, -v79, v27, v28
	v_fma_f32 v29, -v78, v26, v29
	v_add_f32_e32 v28, v29, v28
	v_fma_f32 v29, -v0, v80, v11
	v_fma_f32 v29, -v20, v82, v29
	v_fma_f32 v30, -v19, v81, 0
	v_fma_f32 v29, -v22, v84, v29
	v_fma_f32 v30, -v21, v83, v30
	v_fma_f32 v29, -v24, v86, v29
	v_fma_f32 v30, -v23, v85, v30
	v_fma_f32 v29, -v88, v26, v29
	v_fma_f32 v30, -v87, v25, v30
	v_fma_f32 v29, -v90, v28, v29
	v_fma_f32 v30, -v89, v27, v30
	v_add_f32_e32 v29, v30, v29
	s_waitcnt lgkmcnt(14)
	v_fma_f32 v30, -v19, v93, 0
	v_fma_f32 v31, -v0, v92, v12
	v_fma_f32 v30, -v21, v95, v30
	v_fma_f32 v31, -v20, v94, v31
	s_waitcnt lgkmcnt(13)
	v_fma_f32 v30, -v23, v97, v30
	v_fma_f32 v31, -v22, v96, v31
	v_fma_f32 v30, -v25, v99, v30
	v_fma_f32 v31, -v24, v98, v31
	s_waitcnt lgkmcnt(12)
	v_fma_f32 v30, -v101, v27, v30
	v_fma_f32 v31, -v26, v100, v31
	v_fma_f32 v30, -v103, v29, v30
	v_fma_f32 v31, -v102, v28, v31
	s_waitcnt lgkmcnt(11)
	v_fma_f32 v32, -v0, v104, v13
	v_add_f32_e32 v30, v31, v30
	v_fma_f32 v31, -v19, v105, 0
	v_fma_f32 v32, -v20, v106, v32
	v_fma_f32 v31, -v21, v107, v31
	s_waitcnt lgkmcnt(10)
	v_fma_f32 v32, -v22, v108, v32
	v_fma_f32 v31, -v23, v109, v31
	v_fma_f32 v32, -v24, v110, v32
	v_fma_f32 v31, -v25, v111, v31
	s_waitcnt lgkmcnt(9)
	v_fma_f32 v32, -v26, v112, v32
	v_fma_f32 v31, -v27, v113, v31
	v_fma_f32 v32, -v114, v28, v32
	v_fma_f32 v31, -v115, v29, v31
	s_waitcnt lgkmcnt(8)
	v_fma_f32 v32, -v116, v30, v32
	v_add_f32_e32 v31, v31, v32
	s_waitcnt lgkmcnt(7)
	v_fma_f32 v32, -v19, v119, 0
	v_fma_f32 v33, -v0, v118, v14
	v_fma_f32 v32, -v21, v121, v32
	v_fma_f32 v33, -v20, v120, v33
	s_waitcnt lgkmcnt(6)
	v_fma_f32 v32, -v23, v123, v32
	v_fma_f32 v33, -v22, v122, v33
	v_fma_f32 v32, -v25, v125, v32
	v_fma_f32 v33, -v24, v124, v33
	s_waitcnt lgkmcnt(5)
	v_fma_f32 v32, -v27, v127, v32
	v_fma_f32 v33, -v26, v126, v33
	v_fma_f32 v32, -v129, v29, v32
	v_fma_f32 v33, -v28, v128, v33
	s_waitcnt lgkmcnt(4)
	v_fma_f32 v32, -v131, v31, v32
	v_fma_f32 v33, -v130, v30, v33
	v_add_f32_e32 v32, v33, v32
	s_waitcnt lgkmcnt(3)
	v_fma_f32 v33, -v0, v132, v15
	v_fma_f32 v33, -v20, v134, v33
	v_fma_f32 v34, -v19, v133, 0
	s_waitcnt lgkmcnt(2)
	v_fma_f32 v33, -v22, v136, v33
	v_fma_f32 v34, -v21, v135, v34
	v_fma_f32 v33, -v24, v138, v33
	v_fma_f32 v34, -v23, v137, v34
	s_waitcnt lgkmcnt(1)
	v_fma_f32 v33, -v26, v140, v33
	v_fma_f32 v34, -v25, v139, v34
	v_fma_f32 v33, -v28, v142, v33
	v_fma_f32 v34, -v27, v141, v34
	s_waitcnt lgkmcnt(0)
	v_fma_f32 v33, -v30, v144, v33
	v_fma_f32 v34, -v29, v143, v34
	s_waitcnt lgkmcnt(0)
	v_fma_f32 v33, -v146, v32, v33
	v_fma_f32 v34, -v145, v31, v34
	v_add_f32_e32 v40, v34, v33
	v_mov_b32_dpp v33, v0 quad_perm:[1,1,3,3] row_mask:0xf bank_mask:0xf bound_ctrl:1
	v_mov_b32_dpp v34, v19 quad_perm:[1,1,3,3] row_mask:0xf bank_mask:0xf bound_ctrl:1
	v_mov_b32_dpp v35, v20 quad_perm:[1,1,3,3] row_mask:0xf bank_mask:0xf bound_ctrl:1
	v_mov_b32_dpp v36, v21 quad_perm:[1,1,3,3] row_mask:0xf bank_mask:0xf bound_ctrl:1
	v_mov_b32_dpp v37, v22 quad_perm:[1,1,3,3] row_mask:0xf bank_mask:0xf bound_ctrl:1
	v_mov_b32_dpp v38, v23 quad_perm:[1,1,3,3] row_mask:0xf bank_mask:0xf bound_ctrl:1
	v_mov_b32_dpp v39, v24 quad_perm:[1,1,3,3] row_mask:0xf bank_mask:0xf bound_ctrl:1
	v_mov_b32_dpp v41, v25 quad_perm:[1,1,3,3] row_mask:0xf bank_mask:0xf bound_ctrl:1
	v_mov_b32_dpp v42, v26 quad_perm:[1,1,3,3] row_mask:0xf bank_mask:0xf bound_ctrl:1
	v_mov_b32_dpp v43, v27 quad_perm:[1,1,3,3] row_mask:0xf bank_mask:0xf bound_ctrl:1
	v_mov_b32_dpp v44, v28 quad_perm:[1,1,3,3] row_mask:0xf bank_mask:0xf bound_ctrl:1
	v_mov_b32_dpp v45, v29 quad_perm:[1,1,3,3] row_mask:0xf bank_mask:0xf bound_ctrl:1
	v_mov_b32_dpp v46, v30 quad_perm:[1,1,3,3] row_mask:0xf bank_mask:0xf bound_ctrl:1
	v_mov_b32_dpp v47, v31 quad_perm:[1,1,3,3] row_mask:0xf bank_mask:0xf bound_ctrl:1
	v_mov_b32_dpp v48, v32 quad_perm:[1,1,3,3] row_mask:0xf bank_mask:0xf bound_ctrl:1
	v_mov_b32_dpp v49, v40 quad_perm:[1,1,3,3] row_mask:0xf bank_mask:0xf bound_ctrl:1
	s_and_b64 exec, exec, s[6:7]
	s_cbranch_execz .LBB0_843
	v_cvt_pk_bf16_f32 v19, v19, v34
	v_lshl_add_u32 v34, v16, 1, s5
	v_add3_u32 v34, v34, v17, v18
	v_cvt_pk_bf16_f32 v33, v0, v33
	v_add_u32_e32 v34, 0x5400, v34
	v_cvt_pk_bf16_f32 v40, v40, v49
	v_cvt_pk_bf16_f32 v32, v32, v48
	v_cvt_pk_bf16_f32 v31, v31, v47
	v_cvt_pk_bf16_f32 v30, v30, v46
	v_cvt_pk_bf16_f32 v29, v29, v45
	v_cvt_pk_bf16_f32 v28, v28, v44
	v_cvt_pk_bf16_f32 v27, v27, v43
	v_cvt_pk_bf16_f32 v26, v26, v42
	v_cvt_pk_bf16_f32 v25, v25, v41
	v_cvt_pk_bf16_f32 v24, v24, v39
	v_cvt_pk_bf16_f32 v23, v23, v38
	v_cvt_pk_bf16_f32 v22, v22, v37
	v_cvt_pk_bf16_f32 v21, v21, v36
	v_cvt_pk_bf16_f32 v20, v20, v35
	ds_write2_b32 v34, v33, v19 offset1:12
	ds_write2_b32 v34, v20, v21 offset0:24 offset1:36
	ds_write2_b32 v34, v22, v23 offset0:48 offset1:60
	ds_write2_b32 v34, v24, v25 offset0:72 offset1:84
	ds_write2_b32 v34, v26, v27 offset0:96 offset1:108
	ds_write2_b32 v34, v28, v29 offset0:120 offset1:132
	ds_write2_b32 v34, v30, v31 offset0:144 offset1:156
	ds_write2_b32 v34, v32, v40 offset0:168 offset1:180
	s_branch .LBB0_843
